# row-sum zero seed folded away: first-block running sum written directly (4 VALU per job fewer) on top of the stacked attention trims
# baseline (speedup 1.0000x reference)
; #define LAS __attribute__((address_space(3)))
; __device__ __forceinline__ void att_block(const bf16x8 (&kf)[4], const bf16x8 (&qf)[4], const bf16x8 (&va)[4], f32x16& o0, f32x16& o1, float& mrun, float& lrun, bool domask, int lo_, int hi_) {
;     f32x16 st;
; #pragma unroll
;     for (int i = 0; i < 16; ++i) st[i] = 0.f;
; #pragma unroll
;     for (int kk = 0; kk < 4; ++kk) st = __builtin_amdgcn_mfma_f32_32x32x16_bf16(kf[kk], qf[kk], st, 0, 0, 0);
;     if (domask) {
;         asm volatile("" : "+v"(lo_), "+v"(hi_));
; #pragma unroll
;         for (int i = 0; i < 16; ++i) { const int ci = (i & 3) + 8 * (i >> 2); st[i] = ((ci - lo_) | (hi_ - ci)) < 0 ? -INFINITY : st[i]; }
;     }
;     float bmax = -INFINITY;
; #pragma unroll
;     for (int i = 0; i < 16; ++i) bmax = fmaxf(bmax, st[i]);
;     bmax = fmaxf(bmax, __shfl_xor(bmax, 32));
;     const float mnew = fmaxf(mrun, bmax);
;     float lsum = 0.f;
; #pragma unroll
;     for (int i = 0; i < 16; ++i) { st[i] = __builtin_amdgcn_exp2f(st[i] - mnew); lsum += st[i]; }
;     lsum += __shfl_xor(lsum, 32);
;     const float alpha = __builtin_amdgcn_exp2f(mrun - mnew);
;     lrun = lrun * alpha + lsum; mrun = mnew;
; #pragma unroll
;     for (int i = 0; i < 16; ++i) { o0[i] *= alpha; o1[i] *= alpha; }
; #pragma unroll
;     for (int s = 0; s < 2; ++s) { v4u w; w.x = pk2(st[8 * s], st[8 * s + 1]); w.y = pk2(st[8 * s + 2], st[8 * s + 3]); w.z = pk2(st[8 * s + 4], st[8 * s + 5]); w.w = pk2(st[8 * s + 6], st[8 * s + 7]);
;         const bf16x8 pb = __builtin_bit_cast(bf16x8, w);
;         o0 = __builtin_amdgcn_mfma_f32_32x32x16_bf16(va[2 * s], pb, o0, 0, 0, 0);
;         o1 = __builtin_amdgcn_mfma_f32_32x32x16_bf16(va[2 * s + 1], pb, o1, 0, 0, 0); }
; }
; __device__ __forceinline__ void att_phase(unsigned char* ws, LAS unsigned char* lds, int lane, int wave, int G) {
;     ...
;         for (int kb = 0; kb < 6; ++kb) {
;             asm volatile("s_waitcnt vmcnt(0)" ::: "memory");
;             if (kb < 5) ATT_DMA_KV(P, kb + 1, sb ^ 1);
;             else if (hn) ATT_DMA_KV(N, 0, sb ^ 1);
;             bf16x8 kf[4], va[4];
; #pragma unroll
;             for (int kk = 0; kk < 4; ++kk) kf[kk] = *(LAS const bf16x8*)(kfb + sb * 4096 + (((2 * kk + h) ^ (qc & 7)) << 4));
;             LAS const unsigned char* trs = trb + 8192 + sb * 4096;
; #pragma unroll
;             for (int s = 0; s < 2; ++s) {
.Lmk_done_0:
	s_nop 0
	s_nop 0
	v_max3_f32 v12, v0, s59, v1
	v_max3_f32 v12, v12, v2, v3
	v_max3_f32 v12, v12, v4, v5
	v_max3_f32 v12, v12, v6, v7
	v_max3_f32 v12, v12, v8, v9
	v_xor_b32_e32 v13, 32, v206
	v_max3_f32 v12, v12, v10, v11
	v_cmp_lt_i32_e32 vcc, v13, v208
	v_max3_f32 v12, v12, v56, v57
	v_max3_f32 v12, v12, v58, v59
	v_cndmask_b32_e32 v13, v206, v13, vcc
	v_lshlrev_b32_e32 v201, 2, v13
	ds_bpermute_b32 v13, v201, v12
	s_mov_b32 s59, 0xf149f2ca
	s_waitcnt lgkmcnt(0)
	v_max3_f32 v50, v12, v13, s59
	v_sub_f32_e32 v0, v0, v50
	v_exp_f32_e32 v16, v0
	v_sub_f32_e32 v0, v1, v50
	v_exp_f32_e32 v17, v0
	v_sub_f32_e32 v1, v2, v50
	v_exp_f32_e32 v18, v1
	v_sub_f32_e32 v1, v3, v50
	v_exp_f32_e32 v19, v1
	v_sub_f32_e32 v1, v4, v50
	v_exp_f32_e32 v20, v1
	v_sub_f32_e32 v1, v5, v50
	v_add_f32_e32 v0, v17, v16
	v_exp_f32_e32 v21, v1
	v_sub_f32_e32 v1, v6, v50
	v_add_f32_e32 v0, v18, v0
	v_exp_f32_e32 v22, v1
	v_sub_f32_e32 v1, v7, v50
	v_add_f32_e32 v0, v19, v0
	v_exp_f32_e32 v23, v1
	v_sub_f32_e32 v1, v8, v50
	v_add_f32_e32 v0, v20, v0
	v_exp_f32_e32 v60, v1
	v_sub_f32_e32 v1, v9, v50
	v_add_f32_e32 v0, v21, v0
	v_exp_f32_e32 v61, v1
	v_add_f32_e32 v0, v22, v0
	v_add_f32_e32 v0, v23, v0
	v_add_f32_e32 v0, v60, v0
	v_add_f32_e32 v62, v61, v0
	v_sub_f32_e32 v1, v10, v50
	v_cvt_pk_bf16_f32 v52, v16, v17
	v_sub_f32_e32 v16, v56, v50
	v_exp_f32_e32 v63, v1
	v_sub_f32_e32 v64, v11, v50
	v_cvt_pk_bf16_f32 v53, v18, v19
	v_cvt_pk_bf16_f32 v54, v20, v21
	v_cvt_pk_bf16_f32 v55, v22, v23
	v_exp_f32_e32 v56, v16
	v_sub_f32_e32 v16, v57, v50
	v_mfma_f32_32x32x16_bf16 v[18:33], v[34:37], v[52:55], 0
	v_exp_f32_e32 v57, v16
	v_sub_f32_e32 v34, v58, v50
	v_exp_f32_e32 v64, v64
	v_cvt_pk_bf16_f32 v36, v56, v57
	s_nop 1
	v_exp_f32_e32 v1, v34
	v_sub_f32_e32 v34, v59, v50
	v_mfma_f32_32x32x16_bf16 v[2:17], v[38:41], v[52:55], 0
	v_exp_f32_e32 v38, v34
	v_add_f32_e32 v39, v63, v62
	v_add_f32_e32 v39, v64, v39
	v_cvt_pk_bf16_f32 v34, v60, v61
	v_cvt_pk_bf16_f32 v35, v63, v64
	v_cvt_pk_bf16_f32 v37, v1, v38
	v_add_f32_e32 v39, v56, v39
	v_add_f32_e32 v39, v57, v39
	v_mfma_f32_32x32x16_bf16 v[18:33], v[42:45], v[34:37], v[18:33]
	v_add_f32_e32 v1, v1, v39
	v_add_f32_e32 v1, v38, v1
	ds_bpermute_b32 v232, v201, v1
	v_mfma_f32_32x32x16_bf16 v[2:17], v[46:49], v[34:37], v[2:17]
	v_add_u32_e32 v38, s6, v51
	v_max_i32_e32 v164, 0, v38
	s_mov_b32 m0, s33
	s_waitcnt vmcnt(0)
	v_lshl_add_u32 v36, v164, 7, v180
	v_add_u32_e32 v38, s6, v38
	global_load_lds_dwordx4 v36, s[98:99]
	v_lshl_add_u32 v34, v164, 7, v182
	s_mov_b32 m0, s44
	v_max_i32_e32 v164, 0, v38
	global_load_lds_dwordx4 v34, s[100:101]
	v_lshl_add_u32 v36, v164, 7, v180
	s_mov_b32 m0, s66
	v_add_u32_e32 v38, s6, v38
	global_load_lds_dwordx4 v36, s[98:99]
	v_lshl_add_u32 v34, v164, 7, v182
	s_mov_b32 m0, s67
	v_max_i32_e32 v164, 0, v38
	global_load_lds_dwordx4 v34, s[100:101]
	v_lshl_add_u32 v36, v164, 7, v180
	s_mov_b32 m0, s48
	v_lshl_add_u32 v34, v164, 7, v182
	global_load_lds_dwordx4 v36, s[98:99]
	s_mov_b32 m0, s49
	v_readlane_b32 s59, v254, 27
	global_load_lds_dwordx4 v34, s[100:101]
	v_add_u32_e32 v34, s6, v38
	v_max_i32_e32 v164, 0, v34
	v_lshl_add_u32 v36, v164, 7, v180
	s_mov_b32 m0, s72
	v_lshl_add_u32 v34, v164, 7, v182
	global_load_lds_dwordx4 v36, s[98:99]
	s_mov_b32 m0, s59
	s_cmp_gt_i32 s58, 32
	global_load_lds_dwordx4 v34, s[100:101]
	ds_read_b128 v[68:71], v225 offset:4096
	ds_read_b128 v[64:67], v226 offset:4096
	s_waitcnt lgkmcnt(0)
	v_mfma_f32_32x32x16_bf16 v[34:49], v[68:71], v[128:131], 0
	ds_read_b128 v[60:63], v227 offset:4096
	ds_read_b128 v[56:59], v228 offset:4096
	ds_read_b64_tr_b16 v[52:53], v229 offset:12288
	ds_read_b64_tr_b16 v[54:55], v229 offset:13312
	ds_read_b64_tr_b16 v[94:95], v229 offset:13376
	ds_read_b64_tr_b16 v[92:93], v229 offset:12352
	ds_read_b64_tr_b16 v[88:89], v229 offset:14336
	ds_read_b64_tr_b16 v[90:91], v229 offset:15360
	ds_read_b64_tr_b16 v[86:87], v229 offset:15424
	ds_read_b64_tr_b16 v[84:85], v229 offset:14400
	v_mfma_f32_32x32x16_bf16 v[34:49], v[64:67], v[124:127], v[34:49]
	s_waitcnt lgkmcnt(9)
	v_mfma_f32_32x32x16_bf16 v[34:49], v[60:63], v[120:123], v[34:49]
	s_waitcnt lgkmcnt(8)
	v_mfma_f32_32x32x16_bf16 v[34:49], v[56:59], v[116:119], v[34:49]
	s_cbranch_scc0 .LBB0_82
	v_sub_u32_e32 v51, v199, v215
	v_mov_b32_e32 v72, v216
	s_nop 0
	s_nop 1
	v_cmp_ge_i32_e32 vcc, 0, v51
	v_cmp_ge_i32_e64 s[24:25], 1, v51
	v_cmp_ge_i32_e64 s[26:27], 2, v51
	v_cmp_ge_i32_e64 s[28:29], 3, v51
	s_nop 1
	v_cndmask_b32_e32 v34, v211, v34, vcc
	v_cmp_ge_i32_e32 vcc, 8, v51
	v_cndmask_b32_e64 v35, v211, v35, s[24:25]
	v_cmp_ge_i32_e64 s[24:25], 9, v51
	v_cndmask_b32_e64 v36, v211, v36, s[26:27]
	v_cmp_ge_i32_e64 s[26:27], 10, v51
	v_cndmask_b32_e64 v37, v211, v37, s[28:29]
	v_cmp_ge_i32_e64 s[28:29], 11, v51
	v_cndmask_b32_e32 v38, v211, v38, vcc
	v_cmp_ge_i32_e32 vcc, 16, v51
	v_cndmask_b32_e64 v39, v211, v39, s[24:25]
	v_cmp_ge_i32_e64 s[24:25], 17, v51
	v_cndmask_b32_e64 v40, v211, v40, s[26:27]
	v_cmp_ge_i32_e64 s[26:27], 18, v51
	v_cndmask_b32_e64 v41, v211, v41, s[28:29]
	v_cmp_ge_i32_e64 s[28:29], 19, v51
	v_cndmask_b32_e32 v42, v211, v42, vcc
	v_cmp_ge_i32_e32 vcc, 24, v51
	v_cndmask_b32_e64 v43, v211, v43, s[24:25]
	v_cmp_ge_i32_e64 s[24:25], 25, v51
	v_cndmask_b32_e64 v44, v211, v44, s[26:27]
	v_cmp_ge_i32_e64 s[26:27], 26, v51
	v_cndmask_b32_e64 v45, v211, v45, s[28:29]
	v_cmp_ge_i32_e64 s[28:29], 27, v51
	v_cndmask_b32_e32 v46, v211, v46, vcc
	v_cndmask_b32_e64 v47, v211, v47, s[24:25]
	v_cndmask_b32_e64 v48, v211, v48, s[26:27]
	v_cndmask_b32_e64 v49, v211, v49, s[28:29]
	s_nop 0
	s_nop 1

; #define LAS __attribute__((address_space(3)))
; __device__ __forceinline__ void att_block(const bf16x8 (&kf)[4], const bf16x8 (&qf)[4], const bf16x8 (&va)[4], f32x16& o0, f32x16& o1, float& mrun, float& lrun, bool domask, int lo_, int hi_) {
;     f32x16 st;
; #pragma unroll
;     for (int i = 0; i < 16; ++i) st[i] = 0.f;
; #pragma unroll
;     for (int kk = 0; kk < 4; ++kk) st = __builtin_amdgcn_mfma_f32_32x32x16_bf16(kf[kk], qf[kk], st, 0, 0, 0);
;     if (domask) {
;         asm volatile("" : "+v"(lo_), "+v"(hi_));
; #pragma unroll
;         for (int i = 0; i < 16; ++i) { const int ci = (i & 3) + 8 * (i >> 2); st[i] = ((ci - lo_) | (hi_ - ci)) < 0 ? -INFINITY : st[i]; }
;     }
;     float bmax = -INFINITY;
; #pragma unroll
;     for (int i = 0; i < 16; ++i) bmax = fmaxf(bmax, st[i]);
;     bmax = fmaxf(bmax, __shfl_xor(bmax, 32));
;     const float mnew = fmaxf(mrun, bmax);
;     float lsum = 0.f;
; #pragma unroll
;     for (int i = 0; i < 16; ++i) { st[i] = __builtin_amdgcn_exp2f(st[i] - mnew); lsum += st[i]; }
;     lsum += __shfl_xor(lsum, 32);
;     const float alpha = __builtin_amdgcn_exp2f(mrun - mnew);
;     lrun = lrun * alpha + lsum; mrun = mnew;
; #pragma unroll
;     for (int i = 0; i < 16; ++i) { o0[i] *= alpha; o1[i] *= alpha; }
; #pragma unroll
;     for (int s = 0; s < 2; ++s) { v4u w; w.x = pk2(st[8 * s], st[8 * s + 1]); w.y = pk2(st[8 * s + 2], st[8 * s + 3]); w.z = pk2(st[8 * s + 4], st[8 * s + 5]); w.w = pk2(st[8 * s + 6], st[8 * s + 7]);
;         const bf16x8 pb = __builtin_bit_cast(bf16x8, w);
;         o0 = __builtin_amdgcn_mfma_f32_32x32x16_bf16(va[2 * s], pb, o0, 0, 0, 0);
;         o1 = __builtin_amdgcn_mfma_f32_32x32x16_bf16(va[2 * s + 1], pb, o1, 0, 0, 0); }
; }
; __device__ __forceinline__ void att_phase(unsigned char* ws, LAS unsigned char* lds, int lane, int wave, int G) {
;     ...
;         for (int kb = 0; kb < 6; ++kb) {
;             asm volatile("s_waitcnt vmcnt(0)" ::: "memory");
;             if (kb < 5) ATT_DMA_KV(P, kb + 1, sb ^ 1);
;             else if (hn) ATT_DMA_KV(N, 0, sb ^ 1);
;             bf16x8 kf[4], va[4];
; #pragma unroll
;             for (int kk = 0; kk < 4; ++kk) kf[kk] = *(LAS const bf16x8*)(kfb + sb * 4096 + (((2 * kk + h) ^ (qc & 7)) << 4));
;             LAS const unsigned char* trs = trb + 8192 + sb * 4096;
; #pragma unroll
;             for (int s = 0; s < 2; ++s) {
.Lmk_done_2:
	s_nop 0
	v_max3_f32 v18, v2, s59, v3
	v_max3_f32 v18, v18, v4, v5
	v_max3_f32 v18, v18, v6, v7
	v_max3_f32 v18, v18, v8, v9
	v_max3_f32 v18, v18, v10, v11
	v_max3_f32 v18, v18, v12, v13
	v_max3_f32 v18, v18, v14, v15
	v_max3_f32 v18, v18, v16, v17
	ds_bpermute_b32 v19, v201, v18
	s_mov_b32 s59, 0xf149f2ca
	s_waitcnt lgkmcnt(0)
	v_max3_f32 v150, v18, v19, s59
	v_sub_f32_e32 v2, v2, v150
	v_exp_f32_e32 v18, v2
	v_sub_f32_e32 v3, v3, v150
	v_exp_f32_e32 v19, v3
	v_sub_f32_e32 v3, v4, v150
	v_exp_f32_e32 v56, v3
	v_sub_f32_e32 v3, v5, v150
	v_exp_f32_e32 v57, v3
	v_sub_f32_e32 v3, v6, v150
	v_exp_f32_e32 v58, v3
	v_sub_f32_e32 v3, v7, v150
	v_add_f32_e32 v2, v19, v18
	v_exp_f32_e32 v59, v3
	v_sub_f32_e32 v3, v8, v150
	v_add_f32_e32 v2, v56, v2
	v_exp_f32_e32 v60, v3
	v_sub_f32_e32 v3, v9, v150
	v_add_f32_e32 v2, v57, v2
	v_exp_f32_e32 v61, v3
	v_sub_f32_e32 v3, v10, v150
	v_add_f32_e32 v2, v58, v2
	v_exp_f32_e32 v132, v3
	v_sub_f32_e32 v3, v11, v150
	v_add_f32_e32 v2, v59, v2
	v_exp_f32_e32 v133, v3
	v_sub_f32_e32 v3, v12, v150
	v_add_f32_e32 v2, v60, v2
	v_exp_f32_e32 v134, v3
	v_sub_f32_e32 v3, v13, v150
	v_add_f32_e32 v2, v61, v2
	v_exp_f32_e32 v135, v3
	v_sub_f32_e32 v3, v14, v150
	v_add_f32_e32 v2, v132, v2
	v_exp_f32_e32 v136, v3
	v_sub_f32_e32 v3, v15, v150
	v_add_f32_e32 v2, v133, v2
	v_exp_f32_e32 v137, v3
	v_sub_f32_e32 v3, v16, v150
	v_add_f32_e32 v2, v134, v2
	v_exp_f32_e32 v138, v3
	v_sub_f32_e32 v3, v17, v150
	v_add_f32_e32 v2, v135, v2
	v_exp_f32_e32 v139, v3
	v_add_f32_e32 v2, v136, v2
	v_add_f32_e32 v2, v137, v2
	v_add_f32_e32 v2, v138, v2
	v_add_f32_e32 v233, v139, v2
	v_cvt_pk_bf16_f32 v96, v18, v19
	v_cvt_pk_bf16_f32 v97, v56, v57
	v_cvt_pk_bf16_f32 v98, v58, v59
	v_cvt_pk_bf16_f32 v99, v60, v61
	ds_bpermute_b32 v234, v201, v233
	s_nop 0
	v_mfma_f32_32x32x16_bf16 v[68:83], v[52:55], v[96:99], 0
	v_cvt_pk_bf16_f32 v4, v132, v133
	v_cvt_pk_bf16_f32 v5, v134, v135
	v_mfma_f32_32x32x16_bf16 v[52:67], v[92:95], v[96:99], 0
	v_cvt_pk_bf16_f32 v6, v136, v137
	v_cvt_pk_bf16_f32 v7, v138, v139
	s_nop 1
	v_mfma_f32_32x32x16_bf16 v[68:83], v[88:91], v[4:7], v[68:83]
	v_mfma_f32_32x32x16_bf16 v[52:67], v[84:87], v[4:7], v[52:67]
	v_mul_lo_u32 v3, s56, v217
	v_add_u32_e32 v3, s11, v3
	v_max_i32_e32 v164, 0, v3
	s_mov_b32 m0, s57
	s_waitcnt vmcnt(0)
	v_lshl_add_u32 v6, v164, 7, v180
	v_add_u32_e32 v3, s6, v3
	global_load_lds_dwordx4 v6, s[98:99]
	v_lshl_add_u32 v4, v164, 7, v182
	s_mov_b32 m0, s7
	v_max_i32_e32 v164, 0, v3
	global_load_lds_dwordx4 v4, s[100:101]
	v_readlane_b32 s59, v254, 28
	v_lshl_add_u32 v6, v164, 7, v180
	s_mov_b32 m0, s59
	v_readlane_b32 s59, v254, 29
	v_add_u32_e32 v3, s6, v3
	global_load_lds_dwordx4 v6, s[98:99]
	v_lshl_add_u32 v4, v164, 7, v182
	s_mov_b32 m0, s59
	v_max_i32_e32 v164, 0, v3
	global_load_lds_dwordx4 v4, s[100:101]
	v_lshl_add_u32 v6, v164, 7, v180
	s_mov_b32 m0, s15
	v_add_u32_e32 v3, s6, v3
	global_load_lds_dwordx4 v6, s[98:99]
	v_lshl_add_u32 v4, v164, 7, v182
	s_mov_b32 m0, s17
	v_max_i32_e32 v164, 0, v3
	global_load_lds_dwordx4 v4, s[100:101]
	v_lshl_add_u32 v6, v164, 7, v180
	s_mov_b32 m0, s21
	v_readlane_b32 s59, v254, 30
	global_load_lds_dwordx4 v6, s[98:99]
	v_lshl_add_u32 v4, v164, 7, v182
	s_mov_b32 m0, s59
	s_cmpk_lt_i32 s58, 0x41
	global_load_lds_dwordx4 v4, s[100:101]
	ds_read_b128 v[144:147], v225
	ds_read_b128 v[140:143], v226
	s_waitcnt lgkmcnt(0)
	v_mfma_f32_32x32x16_bf16 v[4:19], v[144:147], v[128:131], 0
	ds_read_b128 v[136:139], v227
	ds_read_b128 v[132:135], v228
	ds_read_b64_tr_b16 v[96:97], v229 offset:8192
	ds_read_b64_tr_b16 v[98:99], v229 offset:9216
	ds_read_b64_tr_b16 v[94:95], v229 offset:9280
	ds_read_b64_tr_b16 v[92:93], v229 offset:8256
	ds_read_b64_tr_b16 v[88:89], v229 offset:10240
	ds_read_b64_tr_b16 v[90:91], v229 offset:11264
	ds_read_b64_tr_b16 v[86:87], v229 offset:11328
	ds_read_b64_tr_b16 v[84:85], v229 offset:10304
	v_mfma_f32_32x32x16_bf16 v[4:19], v[140:143], v[124:127], v[4:19]
	s_waitcnt lgkmcnt(9)
	v_mfma_f32_32x32x16_bf16 v[4:19], v[136:139], v[120:123], v[4:19]
	s_waitcnt lgkmcnt(8)
	v_mfma_f32_32x32x16_bf16 v[4:19], v[132:135], v[116:119], v[4:19]
	s_cbranch_scc1 .LBB0_84
	v_sub_u32_e32 v3, v199, v218
	v_mov_b32_e32 v149, v219
	s_nop 0
	s_nop 1
	v_cmp_ge_i32_e32 vcc, 0, v3
	v_cmp_ge_i32_e64 s[24:25], 1, v3
	v_cmp_ge_i32_e64 s[26:27], 2, v3
	v_cmp_ge_i32_e64 s[28:29], 3, v3
	s_nop 1
	v_cndmask_b32_e32 v4, v211, v4, vcc
	v_cmp_ge_i32_e32 vcc, 8, v3
	v_cndmask_b32_e64 v5, v211, v5, s[24:25]
	v_cmp_ge_i32_e64 s[24:25], 9, v3
	v_cndmask_b32_e64 v6, v211, v6, s[26:27]
	v_cmp_ge_i32_e64 s[26:27], 10, v3
	v_cndmask_b32_e64 v7, v211, v7, s[28:29]
	v_cmp_ge_i32_e64 s[28:29], 11, v3
	v_cndmask_b32_e32 v8, v211, v8, vcc
	v_cmp_ge_i32_e32 vcc, 16, v3
	v_cndmask_b32_e64 v9, v211, v9, s[24:25]
	v_cmp_ge_i32_e64 s[24:25], 17, v3
	v_cndmask_b32_e64 v10, v211, v10, s[26:27]
	v_cmp_ge_i32_e64 s[26:27], 18, v3
	v_cndmask_b32_e64 v11, v211, v11, s[28:29]
	v_cmp_ge_i32_e64 s[28:29], 19, v3
	v_cndmask_b32_e32 v12, v211, v12, vcc
	v_cmp_ge_i32_e32 vcc, 24, v3
	v_cndmask_b32_e64 v13, v211, v13, s[24:25]
	v_cmp_ge_i32_e64 s[24:25], 25, v3
	v_cndmask_b32_e64 v14, v211, v14, s[26:27]
	v_cmp_ge_i32_e64 s[26:27], 26, v3
	v_cndmask_b32_e64 v15, v211, v15, s[28:29]
	v_cmp_ge_i32_e64 s[28:29], 27, v3
	v_cndmask_b32_e32 v16, v211, v16, vcc
	v_cndmask_b32_e64 v17, v211, v17, s[24:25]
	v_cndmask_b32_e64 v18, v211, v18, s[26:27]
	v_cndmask_b32_e64 v19, v211, v19, s[28:29]
	s_nop 0
	s_nop 1

; __device__ __forceinline__ void att_block(const bf16x8 (&kf)[4], const bf16x8 (&qf)[4], const bf16x8 (&va)[4], f32x16& o0, f32x16& o1, float& mrun, float& lrun, bool domask, int lo_, int hi_) {
;     ...
;     lrun = lrun * alpha + lsum; mrun = mnew;
; __device__ __forceinline__ void att_merge(f32x16& o0, f32x16& o1, float mrun, float lrun, int qpos, int brmode, bf16* OPh, float* MLh, bf16* outp, int h) {
;     bf16* op = OPh + (size_t)qpos * 64 + 8 * h;
;     if (brmode != 0) {
;         const f32x2v mlp = gld<f32x2v>(MLh + 2 * (size_t)qpos);
;         v4u pv[4];
; #pragma unroll
;         for (int g = 0; g < 4; ++g) pv[g] = gld<v4u>(op + 16 * g);
;         const float mnew = fmaxf(mrun, mlp.x), ao = __builtin_amdgcn_exp2f(mlp.x - mnew), an = __builtin_amdgcn_exp2f(mrun - mnew);
;         lrun = lrun * an + mlp.y * ao; mrun = mnew;
; #pragma unroll
;         for (int g = 0; g < 4; ++g) {
;             const auto rx = __builtin_amdgcn_permlane32_swap(pv[g].x, pv[g].z, false, false);
;             const auto ry = __builtin_amdgcn_permlane32_swap(pv[g].y, pv[g].w, false, false);
;             const unsigned wa[2] = {rx[0], ry[0]}, wb[2] = {rx[1], ry[1]};
; #pragma unroll
;             for (int j = 0; j < 2; ++j) {
;                 const float a0 = __builtin_bit_cast(float, wa[j] << 16), a1 = __builtin_bit_cast(float, wa[j] & 0xffff0000u);
;                 const float b0 = __builtin_bit_cast(float, wb[j] << 16), b1 = __builtin_bit_cast(float, wb[j] & 0xffff0000u);
;                 if (g < 2) { o0[8 * g + 2 * j] = o0[8 * g + 2 * j] * an + a0 * ao; o0[8 * g + 2 * j + 1] = o0[8 * g + 2 * j + 1] * an + a1 * ao;
;                              o0[8 * g + 4 + 2 * j] = o0[8 * g + 4 + 2 * j] * an + b0 * ao; o0[8 * g + 4 + 2 * j + 1] = o0[8 * g + 4 + 2 * j + 1] * an + b1 * ao; }
;                 else { const int e = 8 * (g - 2);
;                        o1[e + 2 * j] = o1[e + 2 * j] * an + a0 * ao; o1[e + 2 * j + 1] = o1[e + 2 * j + 1] * an + a1 * ao;
;                        o1[e + 4 + 2 * j] = o1[e + 4 + 2 * j] * an + b0 * ao; o1[e + 4 + 2 * j + 1] = o1[e + 4 + 2 * j + 1] * an + b1 * ao; }
;             }
;         }
;     }
.LBB0_98:
	v_add_f32_e32 v0, v1, v232
	v_add_f32_e32 v1, v235, v236
	s_lshl_b64 s[6:7], s[12:13], 7
	s_lshl_b64 s[14:15], s[12:13], 3
	v_fmac_f32_e32 v1, v0, v188
	v_add_f32_e32 v0, v239, v240
	s_add_u32 s12, s38, s6
	v_fmac_f32_e32 v0, v1, v192
	v_add_f32_e32 v1, v243, v244
	s_addc_u32 s13, s41, s7
	s_waitcnt lgkmcnt(0)
	v_fmac_f32_e32 v1, v0, v196
	v_add_f32_e32 v80, v246, v247
	s_add_u32 s6, s42, s14
	v_fmac_f32_e32 v80, v1, v202
	s_addc_u32 s7, s43, s15
	v_mul_lo_u32 v0, s56, v189
	v_add_u32_e32 v0, s11, v0
	v_ashrrev_i32_e32 v1, 31, v0
	s_cmp_lg_u32 s20, 0
	v_lshlrev_b64 v[68:69], 7, v[0:1]
	s_cselect_b64 s[14:15], -1, 0
	v_lshl_add_u64 v[82:83], s[12:13], 0, v[68:69]
	s_and_b64 vcc, exec, s[14:15]
	s_cbranch_vccz .LBB0_100
	v_lshl_add_u64 v[68:69], v[184:185], 1, v[82:83]
	v_lshl_add_u64 v[70:71], v[0:1], 3, s[6:7]
	global_load_dwordx2 v[84:85], v[70:71], off
	global_load_dwordx4 v[88:91], v[68:69], off
	global_load_dwordx4 v[94:97], v[68:69], off offset:32
	global_load_dwordx4 v[72:75], v[68:69], off offset:64
	s_nop 0
	global_load_dwordx4 v[68:71], v[68:69], off offset:96
	v_max_f32_e32 v86, v200, v200
	v_mov_b32_e32 v138, v67
	s_waitcnt vmcnt(4)
	v_max_f32_e32 v81, v84, v84
	v_max_f32_e32 v92, v86, v81
	v_sub_f32_e32 v81, v84, v92
	v_exp_f32_e32 v84, v81
	v_sub_f32_e32 v81, v200, v92
	v_exp_f32_e32 v86, v81
	s_waitcnt vmcnt(3)
	v_mov_b32_e32 v81, v90
	s_nop 1
	v_permlane32_swap_b32_e32 v88, v81
	v_mov_b32_e32 v87, v91
	v_and_b32_e32 v91, 0xffff0000, v81
	v_lshlrev_b32_e32 v90, 16, v81
	s_waitcnt vmcnt(2)
	v_mov_b32_e32 v81, v96
	v_mov_b32_e32 v93, v97
	v_permlane32_swap_b32_e32 v89, v87
	v_permlane32_swap_b32_e32 v94, v81
	v_permlane32_swap_b32_e32 v95, v93
	v_and_b32_e32 v135, 0xffff0000, v89
	v_lshlrev_b32_e32 v134, 16, v89
	v_and_b32_e32 v97, 0xffff0000, v81
	v_lshlrev_b32_e32 v96, 16, v81
	v_lshlrev_b32_e32 v81, 16, v93
	v_and_b32_e32 v137, 0xffff0000, v95
	v_lshlrev_b32_e32 v136, 16, v95
	v_and_b32_e32 v99, 0xffff0000, v88
	v_lshlrev_b32_e32 v98, 16, v88
	v_pk_mul_f32 v[88:89], v[84:85], v[134:135] op_sel_hi:[0,1]
	v_and_b32_e32 v135, 0xffff0000, v94
	v_lshlrev_b32_e32 v134, 16, v94
	v_pk_mul_f32 v[94:95], v[84:85], v[136:137] op_sel_hi:[0,1]
	v_mul_f32_e32 v136, v84, v81
	s_waitcnt vmcnt(1)
	v_mov_b32_e32 v81, v75
	v_and_b32_e32 v133, 0xffff0000, v87
	v_lshlrev_b32_e32 v132, 16, v87
	v_and_b32_e32 v87, 0xffff0000, v93
	v_permlane32_swap_b32_e32 v73, v81
	v_pk_fma_f32 v[62:63], v[62:63], v[86:87], v[94:95] op_sel_hi:[1,0,1]
	v_and_b32_e32 v95, 0xffff0000, v81
	v_lshlrev_b32_e32 v94, 16, v81
	s_waitcnt vmcnt(0)
	v_mov_b32_e32 v81, v71
	v_pk_mul_f32 v[90:91], v[84:85], v[90:91] op_sel_hi:[0,1]
	v_pk_mul_f32 v[96:97], v[84:85], v[96:97] op_sel_hi:[0,1]
	v_permlane32_swap_b32_e32 v72, v74
	v_permlane32_swap_b32_e32 v68, v70
	v_permlane32_swap_b32_e32 v69, v81
	v_pk_mul_f32 v[98:99], v[84:85], v[98:99] op_sel_hi:[0,1]
	v_pk_mul_f32 v[132:133], v[84:85], v[132:133] op_sel_hi:[0,1]
	v_pk_mul_f32 v[134:135], v[84:85], v[134:135] op_sel_hi:[0,1]
	v_mov_b32_e32 v139, v84
	v_pk_fma_f32 v[54:55], v[54:55], v[86:87], v[88:89] op_sel_hi:[1,0,1]
	v_pk_fma_f32 v[56:57], v[56:57], v[86:87], v[90:91] op_sel_hi:[1,0,1]
	v_pk_fma_f32 v[64:65], v[64:65], v[86:87], v[96:97] op_sel_hi:[1,0,1]
	v_and_b32_e32 v75, 0xffff0000, v74
	v_lshlrev_b32_e32 v74, 16, v74
	v_and_b32_e32 v89, 0xffff0000, v72
	v_lshlrev_b32_e32 v88, 16, v72
	v_and_b32_e32 v91, 0xffff0000, v73
	v_lshlrev_b32_e32 v90, 16, v73
	v_pk_mul_f32 v[72:73], v[84:85], v[94:95] op_sel_hi:[0,1]
	v_and_b32_e32 v71, 0xffff0000, v70
	v_lshlrev_b32_e32 v70, 16, v70
	v_and_b32_e32 v95, 0xffff0000, v68
	v_lshlrev_b32_e32 v94, 16, v68
	v_and_b32_e32 v97, 0xffff0000, v69
	v_lshlrev_b32_e32 v96, 16, v69
	v_pk_mul_f32 v[138:139], v[138:139], v[86:87]
	v_pk_fma_f32 v[52:53], v[52:53], v[86:87], v[98:99] op_sel_hi:[1,0,1]
	v_pk_fma_f32 v[58:59], v[58:59], v[86:87], v[132:133] op_sel_hi:[1,0,1]
	v_pk_fma_f32 v[60:61], v[60:61], v[86:87], v[134:135] op_sel_hi:[1,0,1]
	v_pk_mul_f32 v[88:89], v[84:85], v[88:89] op_sel_hi:[0,1]
	v_pk_mul_f32 v[74:75], v[84:85], v[74:75] op_sel_hi:[0,1]
	v_pk_mul_f32 v[90:91], v[84:85], v[90:91] op_sel_hi:[0,1]
	v_pk_mul_f32 v[94:95], v[84:85], v[94:95] op_sel_hi:[0,1]
	v_pk_mul_f32 v[70:71], v[84:85], v[70:71] op_sel_hi:[0,1]
	v_and_b32_e32 v87, 0xffff0000, v81
	v_lshlrev_b32_e32 v81, 16, v81
	v_pk_mul_f32 v[68:69], v[84:85], v[96:97] op_sel_hi:[0,1]
	v_mov_b32_e32 v98, v51
	v_mov_b32_e32 v99, v84
	v_mul_f32_e32 v96, v84, v81
	v_pk_mul_f32 v[98:99], v[98:99], v[86:87]
	v_pk_fma_f32 v[36:37], v[36:37], v[86:87], v[88:89] op_sel_hi:[1,0,1]
	v_pk_fma_f32 v[38:39], v[38:39], v[86:87], v[90:91] op_sel_hi:[1,0,1]
	v_pk_fma_f32 v[40:41], v[40:41], v[86:87], v[74:75] op_sel_hi:[1,0,1]
	v_pk_fma_f32 v[42:43], v[42:43], v[86:87], v[72:73] op_sel_hi:[1,0,1]
	v_pk_fma_f32 v[44:45], v[44:45], v[86:87], v[94:95] op_sel_hi:[1,0,1]
	v_pk_fma_f32 v[46:47], v[46:47], v[86:87], v[68:69] op_sel_hi:[1,0,1]
	v_pk_fma_f32 v[48:49], v[48:49], v[86:87], v[70:71] op_sel_hi:[1,0,1]
	v_mov_b32_e32 v81, v85
	v_mov_b32_e32 v87, v84
	v_mul_f32_e32 v66, v66, v86
	v_mov_b32_e32 v67, v138
	v_mov_b32_e32 v137, v139
	v_mul_f32_e32 v50, v50, v86
	v_mov_b32_e32 v51, v98
	v_mov_b32_e32 v97, v99
	v_pk_mul_f32 v[68:69], v[80:81], v[86:87]
	v_pk_add_f32 v[66:67], v[66:67], v[136:137]
	v_pk_add_f32 v[50:51], v[50:51], v[96:97]
	v_add_f32_e32 v80, v68, v69
	v_mov_b32_e32 v200, v92

; __device__ __forceinline__ unsigned pk2(float lo, float hi) { return pg8::cvt_pk_bf16(lo, hi); }
; __device__ __forceinline__ void att_block(const bf16x8 (&kf)[4], const bf16x8 (&qf)[4], const bf16x8 (&va)[4], f32x16& o0, f32x16& o1, float& mrun, float& lrun, bool domask, int lo_, int hi_) {
;     ...
;     lrun = lrun * alpha + lsum; mrun = mnew;
; __device__ __forceinline__ void att_merge(f32x16& o0, f32x16& o1, float mrun, float lrun, int qpos, int brmode, bf16* OPh, float* MLh, bf16* outp, int h) {
;     ...
;     float sc = 1.f; bf16* dst = op;
;     if (brmode != 2) { if (h == 0) gst<f32x2v>(MLh + 2 * (size_t)qpos, (f32x2v){mrun, lrun}); }
;     else { sc = 1.f / lrun; dst = outp + (size_t)qpos * 1024 + 8 * h; }
; #pragma unroll
;     for (int g = 0; g < 4; ++g) {
;         unsigned ax, ay, bx, by;
;         if (g < 2) { ax = pk2(o0[8 * g] * sc, o0[8 * g + 1] * sc); ay = pk2(o0[8 * g + 2] * sc, o0[8 * g + 3] * sc); bx = pk2(o0[8 * g + 4] * sc, o0[8 * g + 5] * sc); by = pk2(o0[8 * g + 6] * sc, o0[8 * g + 7] * sc); }
;         else { const int e = 8 * (g - 2); ax = pk2(o1[e] * sc, o1[e + 1] * sc); ay = pk2(o1[e + 2] * sc, o1[e + 3] * sc); bx = pk2(o1[e + 4] * sc, o1[e + 5] * sc); by = pk2(o1[e + 6] * sc, o1[e + 7] * sc); }
;         const auto rx = __builtin_amdgcn_permlane32_swap(ax, bx, false, false);
;         const auto ry = __builtin_amdgcn_permlane32_swap(ay, by, false, false);
;         gst<v4u>(dst + 16 * g, (v4u){rx[0], ry[0], rx[1], ry[1]});
;     }
; __device__ __forceinline__ void att_phase(unsigned char* ws, LAS unsigned char* lds, int lane, int wave, int G) {
;     ...
;         att_merge(oA0, oA1, mA, lA, pos0 + qc * d, brmode, OPh, MLh, outp, h);
;         att_merge(oB0, oB1, mB, lB, pos0 + (32 + qc) * d, brmode, OPh, MLh, outp, h);
.LBB0_106:
	v_add_f32_e32 v1, v233, v234
	v_add_f32_e32 v2, v3, v238
	v_fmac_f32_e32 v2, v1, v190
	v_add_f32_e32 v1, v241, v242
	v_fmac_f32_e32 v1, v2, v194
	v_add_f32_e32 v2, v149, v150
	v_pk_mul_f32 v[58:59], v[58:59], v[70:71] op_sel_hi:[1,0]
	v_pk_mul_f32 v[56:57], v[56:57], v[70:71] op_sel_hi:[1,0]
	v_pk_mul_f32 v[72:73], v[54:55], v[70:71] op_sel_hi:[1,0]
	v_pk_mul_f32 v[74:75], v[52:53], v[70:71] op_sel_hi:[1,0]
	v_fmac_f32_e32 v2, v1, v148
	s_waitcnt lgkmcnt(0)
	v_add_f32_e32 v68, v77, v79
	v_cvt_pk_bf16_f32 v55, v58, v59
	v_cvt_pk_bf16_f32 v54, v56, v57
	v_cvt_pk_bf16_f32 v53, v72, v73
	v_cvt_pk_bf16_f32 v52, v74, v75
	v_fmac_f32_e32 v68, v2, v78
	v_lshl_add_u64 v[2:3], v[184:185], 1, v[82:83]
	v_permlane32_swap_b32_e32 v52, v54
	v_permlane32_swap_b32_e32 v53, v55
	global_store_dwordx4 v[2:3], v[52:55], off
	v_pk_mul_f32 v[56:57], v[64:65], v[70:71] op_sel_hi:[1,0]
	v_pk_mul_f32 v[58:59], v[62:63], v[70:71] op_sel_hi:[1,0]
	v_pk_mul_f32 v[52:53], v[66:67], v[70:71] op_sel_hi:[1,0]
	v_pk_mul_f32 v[60:61], v[60:61], v[70:71] op_sel_hi:[1,0]
	v_cvt_pk_bf16_f32 v55, v52, v53
	v_cvt_pk_bf16_f32 v54, v56, v57
	v_cvt_pk_bf16_f32 v53, v58, v59
	v_cvt_pk_bf16_f32 v52, v60, v61
	s_nop 1
	v_permlane32_swap_b32_e32 v52, v54
	v_permlane32_swap_b32_e32 v53, v55
	global_store_dwordx4 v[2:3], v[52:55], off offset:32
	v_pk_mul_f32 v[42:43], v[42:43], v[70:71] op_sel_hi:[1,0]
	v_pk_mul_f32 v[40:41], v[40:41], v[70:71] op_sel_hi:[1,0]
	v_pk_mul_f32 v[52:53], v[38:39], v[70:71] op_sel_hi:[1,0]
	v_pk_mul_f32 v[54:55], v[36:37], v[70:71] op_sel_hi:[1,0]
	v_cvt_pk_bf16_f32 v39, v42, v43
	v_cvt_pk_bf16_f32 v38, v40, v41
	v_cvt_pk_bf16_f32 v37, v52, v53
	v_cvt_pk_bf16_f32 v36, v54, v55
	s_nop 1
	v_permlane32_swap_b32_e32 v36, v38
	v_permlane32_swap_b32_e32 v37, v39
	v_pk_mul_f32 v[40:41], v[48:49], v[70:71] op_sel_hi:[1,0]
	global_store_dwordx4 v[2:3], v[36:39], off offset:64
	v_pk_mul_f32 v[42:43], v[46:47], v[70:71] op_sel_hi:[1,0]
	v_pk_mul_f32 v[44:45], v[44:45], v[70:71] op_sel_hi:[1,0]
	v_cvt_pk_bf16_f32 v38, v40, v41
	v_lshl_add_u32 v40, s56, 5, v0
	v_pk_mul_f32 v[36:37], v[50:51], v[70:71] op_sel_hi:[1,0]
	v_ashrrev_i32_e32 v41, 31, v40
	v_cvt_pk_bf16_f32 v39, v36, v37
	v_cvt_pk_bf16_f32 v37, v42, v43
	v_cvt_pk_bf16_f32 v36, v44, v45
	v_lshlrev_b64 v[0:1], 7, v[40:41]
	s_nop 0
	v_permlane32_swap_b32_e32 v36, v38
	v_permlane32_swap_b32_e32 v37, v39
	s_andn2_b64 vcc, exec, s[14:15]
	v_lshl_add_u64 v[42:43], s[12:13], 0, v[0:1]
	global_store_dwordx4 v[2:3], v[36:39], off offset:96
	s_cbranch_vccnz .LBB0_108
; __device__ __forceinline__ void att_merge(f32x16& o0, f32x16& o1, float mrun, float lrun, int qpos, int brmode, bf16* OPh, float* MLh, bf16* outp, int h) {
;     ...
;     if (brmode != 0) {
;         const f32x2v mlp = gld<f32x2v>(MLh + 2 * (size_t)qpos);
;         v4u pv[4];
; #pragma unroll
;         for (int g = 0; g < 4; ++g) pv[g] = gld<v4u>(op + 16 * g);
;         const float mnew = fmaxf(mrun, mlp.x), ao = __builtin_amdgcn_exp2f(mlp.x - mnew), an = __builtin_amdgcn_exp2f(mrun - mnew);
;         lrun = lrun * an + mlp.y * ao; mrun = mnew;
; #pragma unroll
;         for (int g = 0; g < 4; ++g) {
;             const auto rx = __builtin_amdgcn_permlane32_swap(pv[g].x, pv[g].z, false, false);
;             const auto ry = __builtin_amdgcn_permlane32_swap(pv[g].y, pv[g].w, false, false);
;             const unsigned wa[2] = {rx[0], ry[0]}, wb[2] = {rx[1], ry[1]};
; #pragma unroll
;             for (int j = 0; j < 2; ++j) {
;                 const float a0 = __builtin_bit_cast(float, wa[j] << 16), a1 = __builtin_bit_cast(float, wa[j] & 0xffff0000u);
;                 const float b0 = __builtin_bit_cast(float, wb[j] << 16), b1 = __builtin_bit_cast(float, wb[j] & 0xffff0000u);
;                 if (g < 2) { o0[8 * g + 2 * j] = o0[8 * g + 2 * j] * an + a0 * ao; o0[8 * g + 2 * j + 1] = o0[8 * g + 2 * j + 1] * an + a1 * ao;
;                              o0[8 * g + 4 + 2 * j] = o0[8 * g + 4 + 2 * j] * an + b0 * ao; o0[8 * g + 4 + 2 * j + 1] = o0[8 * g + 4 + 2 * j + 1] * an + b1 * ao; }
;                 else { const int e = 8 * (g - 2);
;                        o1[e + 2 * j] = o1[e + 2 * j] * an + a0 * ao; o1[e + 2 * j + 1] = o1[e + 2 * j + 1] * an + a1 * ao;
;                        o1[e + 4 + 2 * j] = o1[e + 4 + 2 * j] * an + b0 * ao; o1[e + 4 + 2 * j + 1] = o1[e + 4 + 2 * j + 1] * an + b1 * ao; }
;             }
;         }
;     }
	v_lshl_add_u64 v[0:1], v[184:185], 1, v[42:43]
	v_lshl_add_u64 v[2:3], v[40:41], 3, s[6:7]
	global_load_dwordx2 v[44:45], v[2:3], off
	global_load_dwordx4 v[48:51], v[0:1], off
	global_load_dwordx4 v[54:57], v[0:1], off offset:32
	global_load_dwordx4 v[36:39], v[0:1], off offset:64
	s_nop 0
	global_load_dwordx4 v[0:3], v[0:1], off offset:96
	v_max_f32_e32 v47, v76, v76
	v_mov_b32_e32 v66, v35
	s_waitcnt vmcnt(4)
	v_max_f32_e32 v46, v44, v44
	v_max_f32_e32 v52, v47, v46
	v_sub_f32_e32 v44, v44, v52
	v_exp_f32_e32 v44, v44
	s_waitcnt vmcnt(3)
	v_mov_b32_e32 v47, v50
	v_mov_b32_e32 v53, v51
	v_sub_f32_e32 v46, v76, v52
	v_permlane32_swap_b32_e32 v48, v47
	v_permlane32_swap_b32_e32 v49, v53
	v_exp_f32_e32 v46, v46
	v_and_b32_e32 v51, 0xffff0000, v47
	v_lshlrev_b32_e32 v50, 16, v47
	v_and_b32_e32 v61, 0xffff0000, v53
	v_lshlrev_b32_e32 v60, 16, v53
	s_waitcnt vmcnt(2)
	v_mov_b32_e32 v47, v56
	v_mov_b32_e32 v53, v57
	v_and_b32_e32 v63, 0xffff0000, v49
	v_lshlrev_b32_e32 v62, 16, v49
	v_permlane32_swap_b32_e32 v54, v47
	v_permlane32_swap_b32_e32 v55, v53
	v_and_b32_e32 v59, 0xffff0000, v48
	v_lshlrev_b32_e32 v58, 16, v48
	v_pk_mul_f32 v[48:49], v[44:45], v[62:63] op_sel_hi:[0,1]
	v_and_b32_e32 v57, 0xffff0000, v47
	v_lshlrev_b32_e32 v56, 16, v47
	v_and_b32_e32 v63, 0xffff0000, v54
	v_lshlrev_b32_e32 v62, 16, v54
	v_and_b32_e32 v65, 0xffff0000, v55
	v_lshlrev_b32_e32 v64, 16, v55
	v_pk_mul_f32 v[58:59], v[44:45], v[58:59] op_sel_hi:[0,1]
	v_pk_mul_f32 v[50:51], v[44:45], v[50:51] op_sel_hi:[0,1]
	v_pk_mul_f32 v[60:61], v[44:45], v[60:61] op_sel_hi:[0,1]
	v_pk_mul_f32 v[62:63], v[44:45], v[62:63] op_sel_hi:[0,1]
	v_pk_mul_f32 v[56:57], v[44:45], v[56:57] op_sel_hi:[0,1]
	v_and_b32_e32 v47, 0xffff0000, v53
	v_pk_mul_f32 v[54:55], v[44:45], v[64:65] op_sel_hi:[0,1]
	v_mov_b32_e32 v67, v44
	v_lshlrev_b32_e32 v53, 16, v53
	v_pk_mul_f32 v[66:67], v[66:67], v[46:47]
	v_pk_fma_f32 v[20:21], v[20:21], v[46:47], v[58:59] op_sel_hi:[1,0,1]
	v_pk_fma_f32 v[22:23], v[22:23], v[46:47], v[48:49] op_sel_hi:[1,0,1]
	v_pk_fma_f32 v[24:25], v[24:25], v[46:47], v[50:51] op_sel_hi:[1,0,1]
	v_pk_fma_f32 v[26:27], v[26:27], v[46:47], v[60:61] op_sel_hi:[1,0,1]
	v_pk_fma_f32 v[28:29], v[28:29], v[46:47], v[62:63] op_sel_hi:[1,0,1]
	v_pk_fma_f32 v[30:31], v[30:31], v[46:47], v[54:55] op_sel_hi:[1,0,1]
	v_pk_fma_f32 v[32:33], v[32:33], v[46:47], v[56:57] op_sel_hi:[1,0,1]
	s_waitcnt vmcnt(1)
	v_mov_b32_e32 v47, v39
	v_mul_f32_e32 v64, v44, v53
	s_nop 0
	v_permlane32_swap_b32_e32 v37, v47
	s_waitcnt vmcnt(0)
	v_mov_b32_e32 v53, v3
	v_permlane32_swap_b32_e32 v36, v38
	v_and_b32_e32 v55, 0xffff0000, v47
	v_lshlrev_b32_e32 v54, 16, v47
	v_permlane32_swap_b32_e32 v0, v2
	v_permlane32_swap_b32_e32 v1, v53
	v_and_b32_e32 v39, 0xffff0000, v38
	v_lshlrev_b32_e32 v38, 16, v38
	v_and_b32_e32 v49, 0xffff0000, v36
	v_lshlrev_b32_e32 v48, 16, v36
	v_and_b32_e32 v51, 0xffff0000, v37
	v_lshlrev_b32_e32 v50, 16, v37
	v_pk_mul_f32 v[36:37], v[44:45], v[54:55] op_sel_hi:[0,1]
	v_and_b32_e32 v3, 0xffff0000, v2
	v_lshlrev_b32_e32 v2, 16, v2
	v_and_b32_e32 v55, 0xffff0000, v0
	v_lshlrev_b32_e32 v54, 16, v0
	v_and_b32_e32 v57, 0xffff0000, v1
	v_lshlrev_b32_e32 v56, 16, v1
	v_pk_mul_f32 v[48:49], v[44:45], v[48:49] op_sel_hi:[0,1]
	v_pk_mul_f32 v[38:39], v[44:45], v[38:39] op_sel_hi:[0,1]
	v_pk_mul_f32 v[50:51], v[44:45], v[50:51] op_sel_hi:[0,1]
	v_pk_mul_f32 v[54:55], v[44:45], v[54:55] op_sel_hi:[0,1]
	v_pk_mul_f32 v[2:3], v[44:45], v[2:3] op_sel_hi:[0,1]
	v_and_b32_e32 v47, 0xffff0000, v53
	v_pk_mul_f32 v[0:1], v[44:45], v[56:57] op_sel_hi:[0,1]
	v_mov_b32_e32 v58, v19
	v_mov_b32_e32 v59, v44
	v_lshlrev_b32_e32 v53, 16, v53
	v_pk_mul_f32 v[58:59], v[58:59], v[46:47]
	v_pk_fma_f32 v[4:5], v[4:5], v[46:47], v[48:49] op_sel_hi:[1,0,1]
	v_pk_fma_f32 v[6:7], v[6:7], v[46:47], v[50:51] op_sel_hi:[1,0,1]
	v_pk_fma_f32 v[8:9], v[8:9], v[46:47], v[38:39] op_sel_hi:[1,0,1]
	v_pk_fma_f32 v[10:11], v[10:11], v[46:47], v[36:37] op_sel_hi:[1,0,1]
	v_pk_fma_f32 v[12:13], v[12:13], v[46:47], v[54:55] op_sel_hi:[1,0,1]
	v_pk_fma_f32 v[14:15], v[14:15], v[46:47], v[0:1] op_sel_hi:[1,0,1]
	v_pk_fma_f32 v[16:17], v[16:17], v[46:47], v[2:3] op_sel_hi:[1,0,1]
	v_mov_b32_e32 v69, v45
	v_mov_b32_e32 v47, v44
	v_mul_f32_e32 v34, v34, v46
	v_mov_b32_e32 v35, v66
	v_mov_b32_e32 v65, v67
	v_mul_f32_e32 v18, v18, v46
	v_mul_f32_e32 v56, v44, v53
	v_mov_b32_e32 v19, v58
	v_mov_b32_e32 v57, v59
	v_pk_mul_f32 v[0:1], v[68:69], v[46:47]
	v_pk_add_f32 v[34:35], v[34:35], v[64:65]
	v_pk_add_f32 v[18:19], v[18:19], v[56:57]
	v_add_f32_e32 v68, v0, v1
	v_mov_b32_e32 v76, v52
